# filt_main rewritten by hand: filter-MLP rows via scalar loads as SGPR operands, packed f32 FMA, 8 positions per 16-byte store, second-round items split over all blocks
# speedup vs baseline: 1.0641x; 1.0207x over previous
.Lfilt_fast:
	v_writelane_b32 v92, s8, 0
	v_writelane_b32 v92, s9, 1
	v_writelane_b32 v92, s10, 2
	v_writelane_b32 v92, s11, 3
	v_writelane_b32 v92, s12, 4
	v_writelane_b32 v92, s13, 5
	v_writelane_b32 v92, s14, 6
	v_writelane_b32 v92, s15, 7
	v_writelane_b32 v92, s16, 8
	v_writelane_b32 v92, s17, 9
	v_writelane_b32 v92, s18, 10
	v_writelane_b32 v92, s19, 11
	v_writelane_b32 v92, s20, 12
	v_writelane_b32 v92, s21, 13
	v_writelane_b32 v92, s22, 14
	v_writelane_b32 v92, s23, 15
	v_writelane_b32 v92, s24, 16
	v_writelane_b32 v92, s25, 17
	v_writelane_b32 v92, s26, 18
	v_writelane_b32 v92, s27, 19
	v_writelane_b32 v92, s28, 20
	v_writelane_b32 v92, s29, 21
	v_writelane_b32 v92, s30, 22
	v_writelane_b32 v92, s31, 23
	v_writelane_b32 v92, s32, 24
	v_writelane_b32 v92, s33, 25
	v_writelane_b32 v92, s34, 26
	v_writelane_b32 v92, s35, 27
	v_writelane_b32 v92, s36, 28
	v_writelane_b32 v92, s37, 29
	v_writelane_b32 v92, s38, 30
	v_writelane_b32 v92, s39, 31
	s_mov_b32 s99, 0x3fb8aa3b
	s_mov_b32 s4, s94
	s_mov_b32 s100, 0
	s_movk_i32 s101, 64
	s_waitcnt lgkmcnt(0)
.Lff_item:
	s_lshr_b32 s0, s4, 4
	s_and_b32 s1, s4, 15
	v_readlane_b32 s72, v252, 12
	v_readlane_b32 s73, v252, 13
	v_readlane_b32 s6, v252, 8
	v_readlane_b32 s7, v252, 9
	v_readlane_b32 s74, v252, 10
	v_readlane_b32 s75, v252, 11
	s_cmp_lt_u32 s0, 32
	s_movk_i32 s5, 0xff
	s_cmovk_i32 s5, 0x7ff
	s_cselect_b32 s93, 0, 32
	s_cselect_b32 s98, 0x10000, 0
	s_cselect_b32 s74, s74, s6
	s_cselect_b32 s75, s75, s7
	s_cselect_b32 s3, 13, 10
	s_add_u32 s72, s72, s98
	s_addc_u32 s73, s73, 0
	s_sub_i32 s0, s0, s93
	s_lshl_b32 s0, s0, 6
	s_lshr_b32 s96, s1, 2
	s_and_b32 s96, s96, 1
	s_add_i32 s2, s0, s96
	s_add_i32 s6, s5, 1
	s_add_i32 s93, s6, s0
	s_sub_i32 s98, s6, s0
	s_add_i32 s98, s98, -8
	s_cmp_lg_u32 s96, 0
	s_cselect_b32 s0, s93, s98
	s_lshl_b32 s0, s0, 1
	s_add_u32 s74, s74, s0
	s_addc_u32 s75, s75, 0
	s_lshl_b32 s1, s1, 8
	v_add_u32_e32 v90, s1, v176
	v_lshlrev_b32_e32 v64, 2, v90
	v_and_b32_e32 v91, 0x3ff, v90
	v_lshrrev_b32_e32 v66, 11, v90
	v_lshl_add_u32 v66, v66, 10, v91
	v_lshlrev_b32_e32 v66, s3, v66
	v_cvt_f32_u32_e32 v91, v91
	v_mov_b32_e32 v90, 0xc0447cbd
	v_fmamk_f32 v68, v91, 0xbc44ade8, v90
	v_cvt_f32_u32_e32 v69, s5
	s_mov_b32 s6, s78
	s_mov_b32 s7, s79
	global_load_dword v0, v64, s[6:7]
	s_add_u32 s6, s6, 0x4000
	s_addc_u32 s7, s7, 0
	global_load_dword v1, v64, s[6:7]
	s_add_u32 s6, s6, 0x4000
	s_addc_u32 s7, s7, 0
	global_load_dword v2, v64, s[6:7]
	s_add_u32 s6, s6, 0x4000
	s_addc_u32 s7, s7, 0
	global_load_dword v3, v64, s[6:7]
	s_add_u32 s6, s6, 0x4000
	s_addc_u32 s7, s7, 0
	global_load_dword v4, v64, s[6:7]
	s_add_u32 s6, s6, 0x4000
	s_addc_u32 s7, s7, 0
	global_load_dword v5, v64, s[6:7]
	s_add_u32 s6, s6, 0x4000
	s_addc_u32 s7, s7, 0
	global_load_dword v6, v64, s[6:7]
	s_add_u32 s6, s6, 0x4000
	s_addc_u32 s7, s7, 0
	global_load_dword v7, v64, s[6:7]
	s_add_u32 s6, s6, 0x4000
	s_addc_u32 s7, s7, 0
	global_load_dword v8, v64, s[6:7]
	s_add_u32 s6, s6, 0x4000
	s_addc_u32 s7, s7, 0
	global_load_dword v9, v64, s[6:7]
	s_add_u32 s6, s6, 0x4000
	s_addc_u32 s7, s7, 0
	global_load_dword v10, v64, s[6:7]
	s_add_u32 s6, s6, 0x4000
	s_addc_u32 s7, s7, 0
	global_load_dword v11, v64, s[6:7]
	s_add_u32 s6, s6, 0x4000
	s_addc_u32 s7, s7, 0
	global_load_dword v12, v64, s[6:7]
	s_add_u32 s6, s6, 0x4000
	s_addc_u32 s7, s7, 0
	global_load_dword v13, v64, s[6:7]
	s_add_u32 s6, s6, 0x4000
	s_addc_u32 s7, s7, 0
	global_load_dword v14, v64, s[6:7]
	s_add_u32 s6, s6, 0x4000
	s_addc_u32 s7, s7, 0
	global_load_dword v15, v64, s[6:7]
	s_add_u32 s6, s6, 0x4000
	s_addc_u32 s7, s7, 0
	global_load_dword v16, v64, s[6:7]
	s_add_u32 s6, s6, 0x4000
	s_addc_u32 s7, s7, 0
	global_load_dword v17, v64, s[6:7]
	s_add_u32 s6, s6, 0x4000
	s_addc_u32 s7, s7, 0
	global_load_dword v18, v64, s[6:7]
	s_add_u32 s6, s6, 0x4000
	s_addc_u32 s7, s7, 0
	global_load_dword v19, v64, s[6:7]
	s_add_u32 s6, s6, 0x4000
	s_addc_u32 s7, s7, 0
	global_load_dword v20, v64, s[6:7]
	s_add_u32 s6, s6, 0x4000
	s_addc_u32 s7, s7, 0
	global_load_dword v21, v64, s[6:7]
	s_add_u32 s6, s6, 0x4000
	s_addc_u32 s7, s7, 0
	global_load_dword v22, v64, s[6:7]
	s_add_u32 s6, s6, 0x4000
	s_addc_u32 s7, s7, 0
	global_load_dword v23, v64, s[6:7]
	s_add_u32 s6, s6, 0x4000
	s_addc_u32 s7, s7, 0
	global_load_dword v24, v64, s[6:7]
	s_add_u32 s6, s6, 0x4000
	s_addc_u32 s7, s7, 0
	global_load_dword v25, v64, s[6:7]
	s_add_u32 s6, s6, 0x4000
	s_addc_u32 s7, s7, 0
	global_load_dword v26, v64, s[6:7]
	s_add_u32 s6, s6, 0x4000
	s_addc_u32 s7, s7, 0
	global_load_dword v27, v64, s[6:7]
	s_add_u32 s6, s6, 0x4000
	s_addc_u32 s7, s7, 0
	global_load_dword v28, v64, s[6:7]
	s_add_u32 s6, s6, 0x4000
	s_addc_u32 s7, s7, 0
	global_load_dword v29, v64, s[6:7]
	s_add_u32 s6, s6, 0x4000
	s_addc_u32 s7, s7, 0
	global_load_dword v30, v64, s[6:7]
	s_add_u32 s6, s6, 0x4000
	s_addc_u32 s7, s7, 0
	global_load_dword v31, v64, s[6:7]
	s_add_u32 s6, s6, 0x4000
	s_addc_u32 s7, s7, 0
	global_load_dword v32, v64, s[6:7]
	s_add_u32 s6, s6, 0x4000
	s_addc_u32 s7, s7, 0
	global_load_dword v33, v64, s[6:7]
	s_add_u32 s6, s6, 0x4000
	s_addc_u32 s7, s7, 0
	global_load_dword v34, v64, s[6:7]
	s_add_u32 s6, s6, 0x4000
	s_addc_u32 s7, s7, 0
	global_load_dword v35, v64, s[6:7]
	s_add_u32 s6, s6, 0x4000
	s_addc_u32 s7, s7, 0
	global_load_dword v36, v64, s[6:7]
	s_add_u32 s6, s6, 0x4000
	s_addc_u32 s7, s7, 0
	global_load_dword v37, v64, s[6:7]
	s_add_u32 s6, s6, 0x4000
	s_addc_u32 s7, s7, 0
	global_load_dword v38, v64, s[6:7]
	s_add_u32 s6, s6, 0x4000
	s_addc_u32 s7, s7, 0
	global_load_dword v39, v64, s[6:7]
	s_add_u32 s6, s6, 0x4000
	s_addc_u32 s7, s7, 0
	global_load_dword v40, v64, s[6:7]
	s_add_u32 s6, s6, 0x4000
	s_addc_u32 s7, s7, 0
	global_load_dword v41, v64, s[6:7]
	s_add_u32 s6, s6, 0x4000
	s_addc_u32 s7, s7, 0
	global_load_dword v42, v64, s[6:7]
	s_add_u32 s6, s6, 0x4000
	s_addc_u32 s7, s7, 0
	global_load_dword v43, v64, s[6:7]
	s_add_u32 s6, s6, 0x4000
	s_addc_u32 s7, s7, 0
	global_load_dword v44, v64, s[6:7]
	s_add_u32 s6, s6, 0x4000
	s_addc_u32 s7, s7, 0
	global_load_dword v45, v64, s[6:7]
	s_add_u32 s6, s6, 0x4000
	s_addc_u32 s7, s7, 0
	global_load_dword v46, v64, s[6:7]
	s_add_u32 s6, s6, 0x4000
	s_addc_u32 s7, s7, 0
	global_load_dword v47, v64, s[6:7]
	s_add_u32 s6, s6, 0x4000
	s_addc_u32 s7, s7, 0
	global_load_dword v48, v64, s[6:7]
	s_add_u32 s6, s6, 0x4000
	s_addc_u32 s7, s7, 0
	global_load_dword v49, v64, s[6:7]
	s_add_u32 s6, s6, 0x4000
	s_addc_u32 s7, s7, 0
	global_load_dword v50, v64, s[6:7]
	s_add_u32 s6, s6, 0x4000
	s_addc_u32 s7, s7, 0
	global_load_dword v51, v64, s[6:7]
	s_add_u32 s6, s6, 0x4000
	s_addc_u32 s7, s7, 0
	global_load_dword v52, v64, s[6:7]
	s_add_u32 s6, s6, 0x4000
	s_addc_u32 s7, s7, 0
	global_load_dword v53, v64, s[6:7]
	s_add_u32 s6, s6, 0x4000
	s_addc_u32 s7, s7, 0
	global_load_dword v54, v64, s[6:7]
	s_add_u32 s6, s6, 0x4000
	s_addc_u32 s7, s7, 0
	global_load_dword v55, v64, s[6:7]
	s_add_u32 s6, s6, 0x4000
	s_addc_u32 s7, s7, 0
	global_load_dword v56, v64, s[6:7]
	s_add_u32 s6, s6, 0x4000
	s_addc_u32 s7, s7, 0
	global_load_dword v57, v64, s[6:7]
	s_add_u32 s6, s6, 0x4000
	s_addc_u32 s7, s7, 0
	global_load_dword v58, v64, s[6:7]
	s_add_u32 s6, s6, 0x4000
	s_addc_u32 s7, s7, 0
	global_load_dword v59, v64, s[6:7]
	s_add_u32 s6, s6, 0x4000
	s_addc_u32 s7, s7, 0
	global_load_dword v60, v64, s[6:7]
	s_add_u32 s6, s6, 0x4000
	s_addc_u32 s7, s7, 0
	global_load_dword v61, v64, s[6:7]
	s_add_u32 s6, s6, 0x4000
	s_addc_u32 s7, s7, 0
	global_load_dword v62, v64, s[6:7]
	s_add_u32 s6, s6, 0x4000
	s_addc_u32 s7, s7, 0
	global_load_dword v63, v64, s[6:7]
	v_and_b32_e32 v90, 63, v176
	v_add_u32_e32 v90, s2, v90
	v_cvt_f32_i32_e32 v74, v90
	v_div_scale_f32 v75, s[0:1], v69, v69, -v74
	v_rcp_f32_e32 v76, v75
	s_nop 0
	v_fma_f32 v77, -v75, v76, 1.0
	v_fmac_f32_e32 v76, v77, v76
	v_div_scale_f32 v77, vcc, -v74, v69, -v74
	v_mul_f32_e32 v90, v77, v76
	v_fma_f32 v91, -v75, v90, v77
	v_fmac_f32_e32 v90, v91, v76
	v_fma_f32 v75, -v75, v90, v77
	v_div_fmas_f32 v75, v75, v76, v90
	v_div_fixup_f32 v67, v75, v69, -v74
	s_mov_b32 s3, s100
	s_waitcnt vmcnt(0)
.Lff_pp:
	s_add_i32 s98, s2, s3
	s_min_u32 s98, s98, s5
	s_lshl_b32 s98, s98, 8
	s_add_u32 s6, s72, s98
	s_addc_u32 s7, s73, 0
	s_load_dwordx16 s[40:55], s[6:7], 0x0
	s_load_dwordx16 s[56:71], s[6:7], 0x40
	s_waitcnt lgkmcnt(0)
	s_load_dwordx16 s[8:23], s[6:7], 0x80
	s_load_dwordx16 s[24:39], s[6:7], 0xc0
	s_add_i32 s98, s3, 0
	s_nop 0
	v_readlane_b32 s93, v67, s98
	v_pk_mul_f32 v[70:71], s[40:41], v[0:1]
	v_pk_fma_f32 v[70:71], s[42:43], v[2:3], v[70:71]
	v_pk_fma_f32 v[70:71], s[44:45], v[4:5], v[70:71]
	v_pk_fma_f32 v[70:71], s[46:47], v[6:7], v[70:71]
	v_pk_fma_f32 v[70:71], s[48:49], v[8:9], v[70:71]
	v_pk_fma_f32 v[70:71], s[50:51], v[10:11], v[70:71]
	v_pk_fma_f32 v[70:71], s[52:53], v[12:13], v[70:71]
	v_pk_fma_f32 v[70:71], s[54:55], v[14:15], v[70:71]
	v_pk_fma_f32 v[70:71], s[56:57], v[16:17], v[70:71]
	v_pk_fma_f32 v[70:71], s[58:59], v[18:19], v[70:71]
	v_pk_fma_f32 v[70:71], s[60:61], v[20:21], v[70:71]
	v_pk_fma_f32 v[70:71], s[62:63], v[22:23], v[70:71]
	v_pk_fma_f32 v[70:71], s[64:65], v[24:25], v[70:71]
	v_pk_fma_f32 v[70:71], s[66:67], v[26:27], v[70:71]
	v_pk_fma_f32 v[70:71], s[68:69], v[28:29], v[70:71]
	v_pk_fma_f32 v[70:71], s[70:71], v[30:31], v[70:71]
	s_waitcnt lgkmcnt(0)
	s_add_i32 s98, s2, s3
	s_add_i32 s98, s98, 1
	s_min_u32 s98, s98, s5
	s_lshl_b32 s98, s98, 8
	s_add_u32 s0, s72, s98
	s_addc_u32 s1, s73, 0
	s_load_dwordx16 s[40:55], s[0:1], 0x0
	s_load_dwordx16 s[56:71], s[0:1], 0x40
	v_pk_mul_f32 v[72:73], s[8:9], v[32:33]
	v_pk_fma_f32 v[72:73], s[10:11], v[34:35], v[72:73]
	v_pk_fma_f32 v[72:73], s[12:13], v[36:37], v[72:73]
	v_pk_fma_f32 v[72:73], s[14:15], v[38:39], v[72:73]
	v_pk_fma_f32 v[72:73], s[16:17], v[40:41], v[72:73]
	v_pk_fma_f32 v[72:73], s[18:19], v[42:43], v[72:73]
	v_pk_fma_f32 v[72:73], s[20:21], v[44:45], v[72:73]
	v_pk_fma_f32 v[72:73], s[22:23], v[46:47], v[72:73]
	v_pk_fma_f32 v[72:73], s[24:25], v[48:49], v[72:73]
	v_pk_fma_f32 v[72:73], s[26:27], v[50:51], v[72:73]
	v_pk_fma_f32 v[72:73], s[28:29], v[52:53], v[72:73]
	v_pk_fma_f32 v[72:73], s[30:31], v[54:55], v[72:73]
	v_pk_fma_f32 v[72:73], s[32:33], v[56:57], v[72:73]
	v_pk_fma_f32 v[72:73], s[34:35], v[58:59], v[72:73]
	v_pk_fma_f32 v[72:73], s[36:37], v[60:61], v[72:73]
	v_pk_fma_f32 v[72:73], s[38:39], v[62:63], v[72:73]
	v_pk_add_f32 v[70:71], v[70:71], v[72:73]
	v_mul_f32_e64 v74, |v68|, s93
	v_add_f32_e32 v70, v70, v71
	v_mul_f32_e32 v75, 0x3fb8aa3b, v74
	v_fma_f32 v76, v74, s99, -v75
	v_rndne_f32_e32 v77, v75
	v_fmac_f32_e32 v76, 0x32a5705f, v74
	v_sub_f32_e32 v75, v75, v77
	v_add_f32_e32 v75, v75, v76
	v_exp_f32_e32 v75, v75
	v_cvt_i32_f32_e32 v76, v77
	v_cmp_ngt_f32_e32 vcc, 0xc2ce8ed0, v74
	v_ldexp_f32 v75, v75, v76
	s_nop 1
	v_cndmask_b32_e32 v75, 0, v75, vcc
	v_cmp_nlt_f32_e32 vcc, 0x42b17218, v74
	s_nop 1
	v_cndmask_b32_e32 v76, v192, v75, vcc
	v_mul_f32_e32 v78, v76, v70
	s_waitcnt lgkmcnt(0)
	s_load_dwordx16 s[8:23], s[0:1], 0x80
	s_load_dwordx16 s[24:39], s[0:1], 0xc0
	s_add_i32 s98, s3, 1
	s_nop 0
	v_readlane_b32 s93, v67, s98
	v_pk_mul_f32 v[70:71], s[40:41], v[0:1]
	v_pk_fma_f32 v[70:71], s[42:43], v[2:3], v[70:71]
	v_pk_fma_f32 v[70:71], s[44:45], v[4:5], v[70:71]
	v_pk_fma_f32 v[70:71], s[46:47], v[6:7], v[70:71]
	v_pk_fma_f32 v[70:71], s[48:49], v[8:9], v[70:71]
	v_pk_fma_f32 v[70:71], s[50:51], v[10:11], v[70:71]
	v_pk_fma_f32 v[70:71], s[52:53], v[12:13], v[70:71]
	v_pk_fma_f32 v[70:71], s[54:55], v[14:15], v[70:71]
	v_pk_fma_f32 v[70:71], s[56:57], v[16:17], v[70:71]
	v_pk_fma_f32 v[70:71], s[58:59], v[18:19], v[70:71]
	v_pk_fma_f32 v[70:71], s[60:61], v[20:21], v[70:71]
	v_pk_fma_f32 v[70:71], s[62:63], v[22:23], v[70:71]
	v_pk_fma_f32 v[70:71], s[64:65], v[24:25], v[70:71]
	v_pk_fma_f32 v[70:71], s[66:67], v[26:27], v[70:71]
	v_pk_fma_f32 v[70:71], s[68:69], v[28:29], v[70:71]
	v_pk_fma_f32 v[70:71], s[70:71], v[30:31], v[70:71]
	s_waitcnt lgkmcnt(0)
	s_add_i32 s98, s2, s3
	s_add_i32 s98, s98, 2
	s_min_u32 s98, s98, s5
	s_lshl_b32 s98, s98, 8
	s_add_u32 s6, s72, s98
	s_addc_u32 s7, s73, 0
	s_load_dwordx16 s[40:55], s[6:7], 0x0
	s_load_dwordx16 s[56:71], s[6:7], 0x40
	v_pk_mul_f32 v[72:73], s[8:9], v[32:33]
	v_pk_fma_f32 v[72:73], s[10:11], v[34:35], v[72:73]
	v_pk_fma_f32 v[72:73], s[12:13], v[36:37], v[72:73]
	v_pk_fma_f32 v[72:73], s[14:15], v[38:39], v[72:73]
	v_pk_fma_f32 v[72:73], s[16:17], v[40:41], v[72:73]
	v_pk_fma_f32 v[72:73], s[18:19], v[42:43], v[72:73]
	v_pk_fma_f32 v[72:73], s[20:21], v[44:45], v[72:73]
	v_pk_fma_f32 v[72:73], s[22:23], v[46:47], v[72:73]
	v_pk_fma_f32 v[72:73], s[24:25], v[48:49], v[72:73]
	v_pk_fma_f32 v[72:73], s[26:27], v[50:51], v[72:73]
	v_pk_fma_f32 v[72:73], s[28:29], v[52:53], v[72:73]
	v_pk_fma_f32 v[72:73], s[30:31], v[54:55], v[72:73]
	v_pk_fma_f32 v[72:73], s[32:33], v[56:57], v[72:73]
	v_pk_fma_f32 v[72:73], s[34:35], v[58:59], v[72:73]
	v_pk_fma_f32 v[72:73], s[36:37], v[60:61], v[72:73]
	v_pk_fma_f32 v[72:73], s[38:39], v[62:63], v[72:73]
	v_pk_add_f32 v[70:71], v[70:71], v[72:73]
	v_mul_f32_e64 v74, |v68|, s93
	v_add_f32_e32 v70, v70, v71
	v_mul_f32_e32 v75, 0x3fb8aa3b, v74
	v_fma_f32 v76, v74, s99, -v75
	v_rndne_f32_e32 v77, v75
	v_fmac_f32_e32 v76, 0x32a5705f, v74
	v_sub_f32_e32 v75, v75, v77
	v_add_f32_e32 v75, v75, v76
	v_exp_f32_e32 v75, v75
	v_cvt_i32_f32_e32 v76, v77
	v_cmp_ngt_f32_e32 vcc, 0xc2ce8ed0, v74
	v_ldexp_f32 v75, v75, v76
	s_nop 1
	v_cndmask_b32_e32 v75, 0, v75, vcc
	v_cmp_nlt_f32_e32 vcc, 0x42b17218, v74
	s_nop 1
	v_cndmask_b32_e32 v76, v192, v75, vcc
	v_mul_f32_e32 v79, v76, v70
	s_waitcnt lgkmcnt(0)
	s_load_dwordx16 s[8:23], s[6:7], 0x80
	s_load_dwordx16 s[24:39], s[6:7], 0xc0
	s_add_i32 s98, s3, 2
	s_nop 0
	v_readlane_b32 s93, v67, s98
	v_pk_mul_f32 v[70:71], s[40:41], v[0:1]
	v_pk_fma_f32 v[70:71], s[42:43], v[2:3], v[70:71]
	v_pk_fma_f32 v[70:71], s[44:45], v[4:5], v[70:71]
	v_pk_fma_f32 v[70:71], s[46:47], v[6:7], v[70:71]
	v_pk_fma_f32 v[70:71], s[48:49], v[8:9], v[70:71]
	v_pk_fma_f32 v[70:71], s[50:51], v[10:11], v[70:71]
	v_pk_fma_f32 v[70:71], s[52:53], v[12:13], v[70:71]
	v_pk_fma_f32 v[70:71], s[54:55], v[14:15], v[70:71]
	v_pk_fma_f32 v[70:71], s[56:57], v[16:17], v[70:71]
	v_pk_fma_f32 v[70:71], s[58:59], v[18:19], v[70:71]
	v_pk_fma_f32 v[70:71], s[60:61], v[20:21], v[70:71]
	v_pk_fma_f32 v[70:71], s[62:63], v[22:23], v[70:71]
	v_pk_fma_f32 v[70:71], s[64:65], v[24:25], v[70:71]
	v_pk_fma_f32 v[70:71], s[66:67], v[26:27], v[70:71]
	v_pk_fma_f32 v[70:71], s[68:69], v[28:29], v[70:71]
	v_pk_fma_f32 v[70:71], s[70:71], v[30:31], v[70:71]
	s_waitcnt lgkmcnt(0)
	s_add_i32 s98, s2, s3
	s_add_i32 s98, s98, 3
	s_min_u32 s98, s98, s5
	s_lshl_b32 s98, s98, 8
	s_add_u32 s0, s72, s98
	s_addc_u32 s1, s73, 0
	s_load_dwordx16 s[40:55], s[0:1], 0x0
	s_load_dwordx16 s[56:71], s[0:1], 0x40
	v_pk_mul_f32 v[72:73], s[8:9], v[32:33]
	v_pk_fma_f32 v[72:73], s[10:11], v[34:35], v[72:73]
	v_pk_fma_f32 v[72:73], s[12:13], v[36:37], v[72:73]
	v_pk_fma_f32 v[72:73], s[14:15], v[38:39], v[72:73]
	v_pk_fma_f32 v[72:73], s[16:17], v[40:41], v[72:73]
	v_pk_fma_f32 v[72:73], s[18:19], v[42:43], v[72:73]
	v_pk_fma_f32 v[72:73], s[20:21], v[44:45], v[72:73]
	v_pk_fma_f32 v[72:73], s[22:23], v[46:47], v[72:73]
	v_pk_fma_f32 v[72:73], s[24:25], v[48:49], v[72:73]
	v_pk_fma_f32 v[72:73], s[26:27], v[50:51], v[72:73]
	v_pk_fma_f32 v[72:73], s[28:29], v[52:53], v[72:73]
	v_pk_fma_f32 v[72:73], s[30:31], v[54:55], v[72:73]
	v_pk_fma_f32 v[72:73], s[32:33], v[56:57], v[72:73]
	v_pk_fma_f32 v[72:73], s[34:35], v[58:59], v[72:73]
	v_pk_fma_f32 v[72:73], s[36:37], v[60:61], v[72:73]
	v_pk_fma_f32 v[72:73], s[38:39], v[62:63], v[72:73]
	v_pk_add_f32 v[70:71], v[70:71], v[72:73]
	v_mul_f32_e64 v74, |v68|, s93
	v_add_f32_e32 v70, v70, v71
	v_mul_f32_e32 v75, 0x3fb8aa3b, v74
	v_fma_f32 v76, v74, s99, -v75
	v_rndne_f32_e32 v77, v75
	v_fmac_f32_e32 v76, 0x32a5705f, v74
	v_sub_f32_e32 v75, v75, v77
	v_add_f32_e32 v75, v75, v76
	v_exp_f32_e32 v75, v75
	v_cvt_i32_f32_e32 v76, v77
	v_cmp_ngt_f32_e32 vcc, 0xc2ce8ed0, v74
	v_ldexp_f32 v75, v75, v76
	s_nop 1
	v_cndmask_b32_e32 v75, 0, v75, vcc
	v_cmp_nlt_f32_e32 vcc, 0x42b17218, v74
	s_nop 1
	v_cndmask_b32_e32 v76, v192, v75, vcc
	v_mul_f32_e32 v80, v76, v70
	s_waitcnt lgkmcnt(0)
	s_load_dwordx16 s[8:23], s[0:1], 0x80
	s_load_dwordx16 s[24:39], s[0:1], 0xc0
	s_add_i32 s98, s3, 3
	s_nop 0
	v_readlane_b32 s93, v67, s98
	v_pk_mul_f32 v[70:71], s[40:41], v[0:1]
	v_pk_fma_f32 v[70:71], s[42:43], v[2:3], v[70:71]
	v_pk_fma_f32 v[70:71], s[44:45], v[4:5], v[70:71]
	v_pk_fma_f32 v[70:71], s[46:47], v[6:7], v[70:71]
	v_pk_fma_f32 v[70:71], s[48:49], v[8:9], v[70:71]
	v_pk_fma_f32 v[70:71], s[50:51], v[10:11], v[70:71]
	v_pk_fma_f32 v[70:71], s[52:53], v[12:13], v[70:71]
	v_pk_fma_f32 v[70:71], s[54:55], v[14:15], v[70:71]
	v_pk_fma_f32 v[70:71], s[56:57], v[16:17], v[70:71]
	v_pk_fma_f32 v[70:71], s[58:59], v[18:19], v[70:71]
	v_pk_fma_f32 v[70:71], s[60:61], v[20:21], v[70:71]
	v_pk_fma_f32 v[70:71], s[62:63], v[22:23], v[70:71]
	v_pk_fma_f32 v[70:71], s[64:65], v[24:25], v[70:71]
	v_pk_fma_f32 v[70:71], s[66:67], v[26:27], v[70:71]
	v_pk_fma_f32 v[70:71], s[68:69], v[28:29], v[70:71]
	v_pk_fma_f32 v[70:71], s[70:71], v[30:31], v[70:71]
	s_waitcnt lgkmcnt(0)
	s_add_i32 s98, s2, s3
	s_add_i32 s98, s98, 4
	s_min_u32 s98, s98, s5
	s_lshl_b32 s98, s98, 8
	s_add_u32 s6, s72, s98
	s_addc_u32 s7, s73, 0
	s_load_dwordx16 s[40:55], s[6:7], 0x0
	s_load_dwordx16 s[56:71], s[6:7], 0x40
	v_pk_mul_f32 v[72:73], s[8:9], v[32:33]
	v_pk_fma_f32 v[72:73], s[10:11], v[34:35], v[72:73]
	v_pk_fma_f32 v[72:73], s[12:13], v[36:37], v[72:73]
	v_pk_fma_f32 v[72:73], s[14:15], v[38:39], v[72:73]
	v_pk_fma_f32 v[72:73], s[16:17], v[40:41], v[72:73]
	v_pk_fma_f32 v[72:73], s[18:19], v[42:43], v[72:73]
	v_pk_fma_f32 v[72:73], s[20:21], v[44:45], v[72:73]
	v_pk_fma_f32 v[72:73], s[22:23], v[46:47], v[72:73]
	v_pk_fma_f32 v[72:73], s[24:25], v[48:49], v[72:73]
	v_pk_fma_f32 v[72:73], s[26:27], v[50:51], v[72:73]
	v_pk_fma_f32 v[72:73], s[28:29], v[52:53], v[72:73]
	v_pk_fma_f32 v[72:73], s[30:31], v[54:55], v[72:73]
	v_pk_fma_f32 v[72:73], s[32:33], v[56:57], v[72:73]
	v_pk_fma_f32 v[72:73], s[34:35], v[58:59], v[72:73]
	v_pk_fma_f32 v[72:73], s[36:37], v[60:61], v[72:73]
	v_pk_fma_f32 v[72:73], s[38:39], v[62:63], v[72:73]
	v_pk_add_f32 v[70:71], v[70:71], v[72:73]
	v_mul_f32_e64 v74, |v68|, s93
	v_add_f32_e32 v70, v70, v71
	v_mul_f32_e32 v75, 0x3fb8aa3b, v74
	v_fma_f32 v76, v74, s99, -v75
	v_rndne_f32_e32 v77, v75
	v_fmac_f32_e32 v76, 0x32a5705f, v74
	v_sub_f32_e32 v75, v75, v77
	v_add_f32_e32 v75, v75, v76
	v_exp_f32_e32 v75, v75
	v_cvt_i32_f32_e32 v76, v77
	v_cmp_ngt_f32_e32 vcc, 0xc2ce8ed0, v74
	v_ldexp_f32 v75, v75, v76
	s_nop 1
	v_cndmask_b32_e32 v75, 0, v75, vcc
	v_cmp_nlt_f32_e32 vcc, 0x42b17218, v74
	s_nop 1
	v_cndmask_b32_e32 v76, v192, v75, vcc
	v_mul_f32_e32 v81, v76, v70
	s_waitcnt lgkmcnt(0)
	s_load_dwordx16 s[8:23], s[6:7], 0x80
	s_load_dwordx16 s[24:39], s[6:7], 0xc0
	s_add_i32 s98, s3, 4
	s_nop 0
	v_readlane_b32 s93, v67, s98
	v_pk_mul_f32 v[70:71], s[40:41], v[0:1]
	v_pk_fma_f32 v[70:71], s[42:43], v[2:3], v[70:71]
	v_pk_fma_f32 v[70:71], s[44:45], v[4:5], v[70:71]
	v_pk_fma_f32 v[70:71], s[46:47], v[6:7], v[70:71]
	v_pk_fma_f32 v[70:71], s[48:49], v[8:9], v[70:71]
	v_pk_fma_f32 v[70:71], s[50:51], v[10:11], v[70:71]
	v_pk_fma_f32 v[70:71], s[52:53], v[12:13], v[70:71]
	v_pk_fma_f32 v[70:71], s[54:55], v[14:15], v[70:71]
	v_pk_fma_f32 v[70:71], s[56:57], v[16:17], v[70:71]
	v_pk_fma_f32 v[70:71], s[58:59], v[18:19], v[70:71]
	v_pk_fma_f32 v[70:71], s[60:61], v[20:21], v[70:71]
	v_pk_fma_f32 v[70:71], s[62:63], v[22:23], v[70:71]
	v_pk_fma_f32 v[70:71], s[64:65], v[24:25], v[70:71]
	v_pk_fma_f32 v[70:71], s[66:67], v[26:27], v[70:71]
	v_pk_fma_f32 v[70:71], s[68:69], v[28:29], v[70:71]
	v_pk_fma_f32 v[70:71], s[70:71], v[30:31], v[70:71]
	s_waitcnt lgkmcnt(0)
	s_add_i32 s98, s2, s3
	s_add_i32 s98, s98, 5
	s_min_u32 s98, s98, s5
	s_lshl_b32 s98, s98, 8
	s_add_u32 s0, s72, s98
	s_addc_u32 s1, s73, 0
	s_load_dwordx16 s[40:55], s[0:1], 0x0
	s_load_dwordx16 s[56:71], s[0:1], 0x40
	v_pk_mul_f32 v[72:73], s[8:9], v[32:33]
	v_pk_fma_f32 v[72:73], s[10:11], v[34:35], v[72:73]
	v_pk_fma_f32 v[72:73], s[12:13], v[36:37], v[72:73]
	v_pk_fma_f32 v[72:73], s[14:15], v[38:39], v[72:73]
	v_pk_fma_f32 v[72:73], s[16:17], v[40:41], v[72:73]
	v_pk_fma_f32 v[72:73], s[18:19], v[42:43], v[72:73]
	v_pk_fma_f32 v[72:73], s[20:21], v[44:45], v[72:73]
	v_pk_fma_f32 v[72:73], s[22:23], v[46:47], v[72:73]
	v_pk_fma_f32 v[72:73], s[24:25], v[48:49], v[72:73]
	v_pk_fma_f32 v[72:73], s[26:27], v[50:51], v[72:73]
	v_pk_fma_f32 v[72:73], s[28:29], v[52:53], v[72:73]
	v_pk_fma_f32 v[72:73], s[30:31], v[54:55], v[72:73]
	v_pk_fma_f32 v[72:73], s[32:33], v[56:57], v[72:73]
	v_pk_fma_f32 v[72:73], s[34:35], v[58:59], v[72:73]
	v_pk_fma_f32 v[72:73], s[36:37], v[60:61], v[72:73]
	v_pk_fma_f32 v[72:73], s[38:39], v[62:63], v[72:73]
	v_pk_add_f32 v[70:71], v[70:71], v[72:73]
	v_mul_f32_e64 v74, |v68|, s93
	v_add_f32_e32 v70, v70, v71
	v_mul_f32_e32 v75, 0x3fb8aa3b, v74
	v_fma_f32 v76, v74, s99, -v75
	v_rndne_f32_e32 v77, v75
	v_fmac_f32_e32 v76, 0x32a5705f, v74
	v_sub_f32_e32 v75, v75, v77
	v_add_f32_e32 v75, v75, v76
	v_exp_f32_e32 v75, v75
	v_cvt_i32_f32_e32 v76, v77
	v_cmp_ngt_f32_e32 vcc, 0xc2ce8ed0, v74
	v_ldexp_f32 v75, v75, v76
	s_nop 1
	v_cndmask_b32_e32 v75, 0, v75, vcc
	v_cmp_nlt_f32_e32 vcc, 0x42b17218, v74
	s_nop 1
	v_cndmask_b32_e32 v76, v192, v75, vcc
	v_mul_f32_e32 v82, v76, v70
	s_waitcnt lgkmcnt(0)
	s_load_dwordx16 s[8:23], s[0:1], 0x80
	s_load_dwordx16 s[24:39], s[0:1], 0xc0
	s_add_i32 s98, s3, 5
	s_nop 0
	v_readlane_b32 s93, v67, s98
	v_pk_mul_f32 v[70:71], s[40:41], v[0:1]
	v_pk_fma_f32 v[70:71], s[42:43], v[2:3], v[70:71]
	v_pk_fma_f32 v[70:71], s[44:45], v[4:5], v[70:71]
	v_pk_fma_f32 v[70:71], s[46:47], v[6:7], v[70:71]
	v_pk_fma_f32 v[70:71], s[48:49], v[8:9], v[70:71]
	v_pk_fma_f32 v[70:71], s[50:51], v[10:11], v[70:71]
	v_pk_fma_f32 v[70:71], s[52:53], v[12:13], v[70:71]
	v_pk_fma_f32 v[70:71], s[54:55], v[14:15], v[70:71]
	v_pk_fma_f32 v[70:71], s[56:57], v[16:17], v[70:71]
	v_pk_fma_f32 v[70:71], s[58:59], v[18:19], v[70:71]
	v_pk_fma_f32 v[70:71], s[60:61], v[20:21], v[70:71]
	v_pk_fma_f32 v[70:71], s[62:63], v[22:23], v[70:71]
	v_pk_fma_f32 v[70:71], s[64:65], v[24:25], v[70:71]
	v_pk_fma_f32 v[70:71], s[66:67], v[26:27], v[70:71]
	v_pk_fma_f32 v[70:71], s[68:69], v[28:29], v[70:71]
	v_pk_fma_f32 v[70:71], s[70:71], v[30:31], v[70:71]
	s_waitcnt lgkmcnt(0)
	s_add_i32 s98, s2, s3
	s_add_i32 s98, s98, 6
	s_min_u32 s98, s98, s5
	s_lshl_b32 s98, s98, 8
	s_add_u32 s6, s72, s98
	s_addc_u32 s7, s73, 0
	s_load_dwordx16 s[40:55], s[6:7], 0x0
	s_load_dwordx16 s[56:71], s[6:7], 0x40
	v_pk_mul_f32 v[72:73], s[8:9], v[32:33]
	v_pk_fma_f32 v[72:73], s[10:11], v[34:35], v[72:73]
	v_pk_fma_f32 v[72:73], s[12:13], v[36:37], v[72:73]
	v_pk_fma_f32 v[72:73], s[14:15], v[38:39], v[72:73]
	v_pk_fma_f32 v[72:73], s[16:17], v[40:41], v[72:73]
	v_pk_fma_f32 v[72:73], s[18:19], v[42:43], v[72:73]
	v_pk_fma_f32 v[72:73], s[20:21], v[44:45], v[72:73]
	v_pk_fma_f32 v[72:73], s[22:23], v[46:47], v[72:73]
	v_pk_fma_f32 v[72:73], s[24:25], v[48:49], v[72:73]
	v_pk_fma_f32 v[72:73], s[26:27], v[50:51], v[72:73]
	v_pk_fma_f32 v[72:73], s[28:29], v[52:53], v[72:73]
	v_pk_fma_f32 v[72:73], s[30:31], v[54:55], v[72:73]
	v_pk_fma_f32 v[72:73], s[32:33], v[56:57], v[72:73]
	v_pk_fma_f32 v[72:73], s[34:35], v[58:59], v[72:73]
	v_pk_fma_f32 v[72:73], s[36:37], v[60:61], v[72:73]
	v_pk_fma_f32 v[72:73], s[38:39], v[62:63], v[72:73]
	v_pk_add_f32 v[70:71], v[70:71], v[72:73]
	v_mul_f32_e64 v74, |v68|, s93
	v_add_f32_e32 v70, v70, v71
	v_mul_f32_e32 v75, 0x3fb8aa3b, v74
	v_fma_f32 v76, v74, s99, -v75
	v_rndne_f32_e32 v77, v75
	v_fmac_f32_e32 v76, 0x32a5705f, v74
	v_sub_f32_e32 v75, v75, v77
	v_add_f32_e32 v75, v75, v76
	v_exp_f32_e32 v75, v75
	v_cvt_i32_f32_e32 v76, v77
	v_cmp_ngt_f32_e32 vcc, 0xc2ce8ed0, v74
	v_ldexp_f32 v75, v75, v76
	s_nop 1
	v_cndmask_b32_e32 v75, 0, v75, vcc
	v_cmp_nlt_f32_e32 vcc, 0x42b17218, v74
	s_nop 1
	v_cndmask_b32_e32 v76, v192, v75, vcc
	v_mul_f32_e32 v83, v76, v70
	s_waitcnt lgkmcnt(0)
	s_load_dwordx16 s[8:23], s[6:7], 0x80
	s_load_dwordx16 s[24:39], s[6:7], 0xc0
	s_add_i32 s98, s3, 6
	s_nop 0
	v_readlane_b32 s93, v67, s98
	v_pk_mul_f32 v[70:71], s[40:41], v[0:1]
	v_pk_fma_f32 v[70:71], s[42:43], v[2:3], v[70:71]
	v_pk_fma_f32 v[70:71], s[44:45], v[4:5], v[70:71]
	v_pk_fma_f32 v[70:71], s[46:47], v[6:7], v[70:71]
	v_pk_fma_f32 v[70:71], s[48:49], v[8:9], v[70:71]
	v_pk_fma_f32 v[70:71], s[50:51], v[10:11], v[70:71]
	v_pk_fma_f32 v[70:71], s[52:53], v[12:13], v[70:71]
	v_pk_fma_f32 v[70:71], s[54:55], v[14:15], v[70:71]
	v_pk_fma_f32 v[70:71], s[56:57], v[16:17], v[70:71]
	v_pk_fma_f32 v[70:71], s[58:59], v[18:19], v[70:71]
	v_pk_fma_f32 v[70:71], s[60:61], v[20:21], v[70:71]
	v_pk_fma_f32 v[70:71], s[62:63], v[22:23], v[70:71]
	v_pk_fma_f32 v[70:71], s[64:65], v[24:25], v[70:71]
	v_pk_fma_f32 v[70:71], s[66:67], v[26:27], v[70:71]
	v_pk_fma_f32 v[70:71], s[68:69], v[28:29], v[70:71]
	v_pk_fma_f32 v[70:71], s[70:71], v[30:31], v[70:71]
	s_waitcnt lgkmcnt(0)
	s_add_i32 s98, s2, s3
	s_add_i32 s98, s98, 7
	s_min_u32 s98, s98, s5
	s_lshl_b32 s98, s98, 8
	s_add_u32 s0, s72, s98
	s_addc_u32 s1, s73, 0
	s_load_dwordx16 s[40:55], s[0:1], 0x0
	s_load_dwordx16 s[56:71], s[0:1], 0x40
	v_pk_mul_f32 v[72:73], s[8:9], v[32:33]
	v_pk_fma_f32 v[72:73], s[10:11], v[34:35], v[72:73]
	v_pk_fma_f32 v[72:73], s[12:13], v[36:37], v[72:73]
	v_pk_fma_f32 v[72:73], s[14:15], v[38:39], v[72:73]
	v_pk_fma_f32 v[72:73], s[16:17], v[40:41], v[72:73]
	v_pk_fma_f32 v[72:73], s[18:19], v[42:43], v[72:73]
	v_pk_fma_f32 v[72:73], s[20:21], v[44:45], v[72:73]
	v_pk_fma_f32 v[72:73], s[22:23], v[46:47], v[72:73]
	v_pk_fma_f32 v[72:73], s[24:25], v[48:49], v[72:73]
	v_pk_fma_f32 v[72:73], s[26:27], v[50:51], v[72:73]
	v_pk_fma_f32 v[72:73], s[28:29], v[52:53], v[72:73]
	v_pk_fma_f32 v[72:73], s[30:31], v[54:55], v[72:73]
	v_pk_fma_f32 v[72:73], s[32:33], v[56:57], v[72:73]
	v_pk_fma_f32 v[72:73], s[34:35], v[58:59], v[72:73]
	v_pk_fma_f32 v[72:73], s[36:37], v[60:61], v[72:73]
	v_pk_fma_f32 v[72:73], s[38:39], v[62:63], v[72:73]
	v_pk_add_f32 v[70:71], v[70:71], v[72:73]
	v_mul_f32_e64 v74, |v68|, s93
	v_add_f32_e32 v70, v70, v71
	v_mul_f32_e32 v75, 0x3fb8aa3b, v74
	v_fma_f32 v76, v74, s99, -v75
	v_rndne_f32_e32 v77, v75
	v_fmac_f32_e32 v76, 0x32a5705f, v74
	v_sub_f32_e32 v75, v75, v77
	v_add_f32_e32 v75, v75, v76
	v_exp_f32_e32 v75, v75
	v_cvt_i32_f32_e32 v76, v77
	v_cmp_ngt_f32_e32 vcc, 0xc2ce8ed0, v74
	v_ldexp_f32 v75, v75, v76
	s_nop 1
	v_cndmask_b32_e32 v75, 0, v75, vcc
	v_cmp_nlt_f32_e32 vcc, 0x42b17218, v74
	s_nop 1
	v_cndmask_b32_e32 v76, v192, v75, vcc
	v_mul_f32_e32 v84, v76, v70
	s_waitcnt lgkmcnt(0)
	s_load_dwordx16 s[8:23], s[0:1], 0x80
	s_load_dwordx16 s[24:39], s[0:1], 0xc0
	s_add_i32 s98, s3, 7
	s_nop 0
	v_readlane_b32 s93, v67, s98
	v_pk_mul_f32 v[70:71], s[40:41], v[0:1]
	v_pk_fma_f32 v[70:71], s[42:43], v[2:3], v[70:71]
	v_pk_fma_f32 v[70:71], s[44:45], v[4:5], v[70:71]
	v_pk_fma_f32 v[70:71], s[46:47], v[6:7], v[70:71]
	v_pk_fma_f32 v[70:71], s[48:49], v[8:9], v[70:71]
	v_pk_fma_f32 v[70:71], s[50:51], v[10:11], v[70:71]
	v_pk_fma_f32 v[70:71], s[52:53], v[12:13], v[70:71]
	v_pk_fma_f32 v[70:71], s[54:55], v[14:15], v[70:71]
	v_pk_fma_f32 v[70:71], s[56:57], v[16:17], v[70:71]
	v_pk_fma_f32 v[70:71], s[58:59], v[18:19], v[70:71]
	v_pk_fma_f32 v[70:71], s[60:61], v[20:21], v[70:71]
	v_pk_fma_f32 v[70:71], s[62:63], v[22:23], v[70:71]
	v_pk_fma_f32 v[70:71], s[64:65], v[24:25], v[70:71]
	v_pk_fma_f32 v[70:71], s[66:67], v[26:27], v[70:71]
	v_pk_fma_f32 v[70:71], s[68:69], v[28:29], v[70:71]
	v_pk_fma_f32 v[70:71], s[70:71], v[30:31], v[70:71]
	s_waitcnt lgkmcnt(0)
	v_pk_mul_f32 v[72:73], s[8:9], v[32:33]
	v_pk_fma_f32 v[72:73], s[10:11], v[34:35], v[72:73]
	v_pk_fma_f32 v[72:73], s[12:13], v[36:37], v[72:73]
	v_pk_fma_f32 v[72:73], s[14:15], v[38:39], v[72:73]
	v_pk_fma_f32 v[72:73], s[16:17], v[40:41], v[72:73]
	v_pk_fma_f32 v[72:73], s[18:19], v[42:43], v[72:73]
	v_pk_fma_f32 v[72:73], s[20:21], v[44:45], v[72:73]
	v_pk_fma_f32 v[72:73], s[22:23], v[46:47], v[72:73]
	v_pk_fma_f32 v[72:73], s[24:25], v[48:49], v[72:73]
	v_pk_fma_f32 v[72:73], s[26:27], v[50:51], v[72:73]
	v_pk_fma_f32 v[72:73], s[28:29], v[52:53], v[72:73]
	v_pk_fma_f32 v[72:73], s[30:31], v[54:55], v[72:73]
	v_pk_fma_f32 v[72:73], s[32:33], v[56:57], v[72:73]
	v_pk_fma_f32 v[72:73], s[34:35], v[58:59], v[72:73]
	v_pk_fma_f32 v[72:73], s[36:37], v[60:61], v[72:73]
	v_pk_fma_f32 v[72:73], s[38:39], v[62:63], v[72:73]
	v_pk_add_f32 v[70:71], v[70:71], v[72:73]
	v_mul_f32_e64 v74, |v68|, s93
	v_add_f32_e32 v70, v70, v71
	v_mul_f32_e32 v75, 0x3fb8aa3b, v74
	v_fma_f32 v76, v74, s99, -v75
	v_rndne_f32_e32 v77, v75
	v_fmac_f32_e32 v76, 0x32a5705f, v74
	v_sub_f32_e32 v75, v75, v77
	v_add_f32_e32 v75, v75, v76
	v_exp_f32_e32 v75, v75
	v_cvt_i32_f32_e32 v76, v77
	v_cmp_ngt_f32_e32 vcc, 0xc2ce8ed0, v74
	v_ldexp_f32 v75, v75, v76
	s_nop 1
	v_cndmask_b32_e32 v75, 0, v75, vcc
	v_cmp_nlt_f32_e32 vcc, 0x42b17218, v74
	s_nop 1
	v_cndmask_b32_e32 v76, v192, v75, vcc
	v_mul_f32_e32 v85, v76, v70
	s_add_i32 s98, s2, s3
	s_add_i32 s98, s98, 7
	s_cmp_gt_u32 s98, s5
	s_cselect_b32 s98, 0, -1
	v_and_b32_e32 v85, s98, v85
	s_lshl_b32 s0, s3, 1
	s_cmp_lg_u32 s96, 0
	s_cbranch_scc1 .Lff_dir1
	s_sub_u32 s0, s74, s0
	s_subb_u32 s1, s75, 0
	v_cvt_pk_bf16_f32 v86, v85, v84
	v_cvt_pk_bf16_f32 v87, v83, v82
	v_cvt_pk_bf16_f32 v88, v81, v80
	v_cvt_pk_bf16_f32 v89, v79, v78
	s_branch .Lff_store
.Lff_dir1:
	s_add_u32 s0, s74, s0
	s_addc_u32 s1, s75, 0
	v_cvt_pk_bf16_f32 v86, v78, v79
	v_cvt_pk_bf16_f32 v87, v80, v81
	v_cvt_pk_bf16_f32 v88, v82, v83
	v_cvt_pk_bf16_f32 v89, v84, v85
.Lff_store:
	global_store_dwordx4 v66, v[86:89], s[0:1]
	s_add_i32 s3, s3, 8
	s_cmp_lt_u32 s3, s101
	s_cbranch_scc1 .Lff_pp
	s_cmpk_ge_i32 s4, 0x200
	s_cbranch_scc1 .Lff_done
	s_lshr_b32 s4, s94, 3
	s_addk_i32 s4, 0x200
	s_and_b32 s100, s94, 7
	s_lshl_b32 s100, s100, 3
	s_add_i32 s101, s100, 8
	s_branch .Lff_item
.Lff_done:
	v_readlane_b32 s8, v92, 0
	v_readlane_b32 s9, v92, 1
	v_readlane_b32 s10, v92, 2
	v_readlane_b32 s11, v92, 3
	v_readlane_b32 s12, v92, 4
	v_readlane_b32 s13, v92, 5
	v_readlane_b32 s14, v92, 6
	v_readlane_b32 s15, v92, 7
	v_readlane_b32 s16, v92, 8
	v_readlane_b32 s17, v92, 9
	v_readlane_b32 s18, v92, 10
	v_readlane_b32 s19, v92, 11
	v_readlane_b32 s20, v92, 12
	v_readlane_b32 s21, v92, 13
	v_readlane_b32 s22, v92, 14
	v_readlane_b32 s23, v92, 15
	v_readlane_b32 s24, v92, 16
	v_readlane_b32 s25, v92, 17
	v_readlane_b32 s26, v92, 18
	v_readlane_b32 s27, v92, 19
	v_readlane_b32 s28, v92, 20
	v_readlane_b32 s29, v92, 21
	v_readlane_b32 s30, v92, 22
	v_readlane_b32 s31, v92, 23
	v_readlane_b32 s32, v92, 24
	v_readlane_b32 s33, v92, 25
	v_readlane_b32 s34, v92, 26
	v_readlane_b32 s35, v92, 27
	v_readlane_b32 s36, v92, 28
	v_readlane_b32 s37, v92, 29
	v_readlane_b32 s38, v92, 30
	v_readlane_b32 s39, v92, 31
	s_branch .LBB0_555
.LBB0_539:
	s_or_b64 exec, exec, s[8:9]
	v_readlane_b32 s0, v254, 57
	s_cmp_lg_u32 s0, 1
	s_cbranch_scc1 .LBB0_555
	v_readlane_b32 s1, v254, 41
	s_nop 3
	s_cmpk_eq_i32 s1, 0x200
	s_cbranch_scc1 .Lfilt_fast
	v_mov_b32_e32 v0, v176
	s_mov_b32 s4, s94
	s_cmpk_gt_i32 s4, 0x23f
	s_cbranch_scc1 .LBB0_555
	v_readlane_b32 s8, v252, 0
	s_movk_i32 s0, 0x400
	v_ashrrev_i32_e32 v1, 31, v0
	v_readlane_b32 s20, v252, 12
	v_readlane_b32 s21, v252, 13
	v_cmp_gt_i32_e64 s[0:1], s0, v0
	v_add_u32_e32 v10, 0xffffff00, v0
	v_lshlrev_b32_e32 v11, 4, v0
	v_lshl_add_u64 v[2:3], v[0:1], 4, s[20:21]
	v_readlane_b32 s9, v252, 1
	v_readlane_b32 s10, v252, 2
	v_readlane_b32 s11, v252, 3
	v_readlane_b32 s12, v252, 4
	v_readlane_b32 s13, v252, 5
	v_readlane_b32 s14, v252, 6
	v_readlane_b32 s15, v252, 7
	v_readlane_b32 s16, v252, 8
	v_readlane_b32 s17, v252, 9
	v_readlane_b32 s18, v252, 10
	v_readlane_b32 s19, v252, 11
	v_readlane_b32 s22, v252, 14
	v_readlane_b32 s23, v252, 15
	s_branch .LBB0_543
